# P2 epilogue: the 4 bias vectors are loaded at unit start (K-loop shadow) instead of at the epilogue head
# baseline (speedup 1.0000x reference)
.LBB0_201:
	s_lshl_b32 s100, s4, 8
	s_or_b32 s100, s100, s56
	v_lshl_add_u32 v230, v147, 3, s100
	v_ashrrev_i32_e32 v231, 31, v230
	v_lshl_add_u64 v[230:231], v[230:231], 2, s[10:11]
	global_load_dwordx4 v[232:235], v[230:231], off
	global_load_dwordx4 v[236:239], v[230:231], off offset:16
	global_load_dwordx4 v[240:243], v[230:231], off offset:528
	global_load_dwordx4 v[244:247], v[230:231], off offset:512
	s_ashr_i32 s21, s20, 31
	s_lshl_b64 s[22:23], s[20:21], 20
	s_add_u32 s22, s36, s22
	s_addc_u32 s23, s37, s23
	s_and_b64 s[24:25], s[0:1], exec
	s_cselect_b32 s5, s23, s29
	s_cselect_b32 s21, s22, s28
	s_ashr_i32 s19, s18, 31
	s_lshl_b64 s[24:25], s[18:19], 20
	s_add_u32 s24, s62, s24
	s_addc_u32 s25, s63, s25
	s_and_b64 s[34:35], s[0:1], exec
	s_cselect_b32 s19, s25, s31
	s_cselect_b32 s72, s24, s30
	s_add_u32 s28, s28, 0x80080
	s_addc_u32 s29, s29, 0
	s_add_u32 s73, s30, 0x100
	v_mov_b32_e32 v0, 0
	s_addc_u32 s74, s31, 0
	s_mov_b32 s75, -2
	v_mov_b32_e32 v1, v0
	v_mov_b32_e32 v2, v0
	v_mov_b32_e32 v3, v0
	v_mov_b32_e32 v4, v0
	v_mov_b32_e32 v5, v0
	v_mov_b32_e32 v6, v0
	v_mov_b32_e32 v7, v0
	v_mov_b32_e32 v16, v0
	v_mov_b32_e32 v17, v0
	v_mov_b32_e32 v18, v0
	v_mov_b32_e32 v19, v0
	v_mov_b32_e32 v20, v0
	v_mov_b32_e32 v21, v0
	v_mov_b32_e32 v22, v0
	v_mov_b32_e32 v23, v0
	v_mov_b32_e32 v32, v0
	v_mov_b32_e32 v33, v0
	v_mov_b32_e32 v34, v0
	v_mov_b32_e32 v35, v0
	v_mov_b32_e32 v36, v0
	v_mov_b32_e32 v37, v0
	v_mov_b32_e32 v38, v0
	v_mov_b32_e32 v39, v0
	v_mov_b32_e32 v48, v0
	v_mov_b32_e32 v49, v0
	v_mov_b32_e32 v50, v0
	v_mov_b32_e32 v51, v0
	v_mov_b32_e32 v56, v0
	v_mov_b32_e32 v57, v0
	v_mov_b32_e32 v58, v0
	v_mov_b32_e32 v59, v0
	v_mov_b32_e32 v8, v0
	v_mov_b32_e32 v9, v0
	v_mov_b32_e32 v10, v0
	v_mov_b32_e32 v11, v0
	v_mov_b32_e32 v12, v0
	v_mov_b32_e32 v13, v0
	v_mov_b32_e32 v14, v0
	v_mov_b32_e32 v15, v0
	v_mov_b32_e32 v24, v0
	v_mov_b32_e32 v25, v0
	v_mov_b32_e32 v26, v0
	v_mov_b32_e32 v27, v0
	v_mov_b32_e32 v28, v0
	v_mov_b32_e32 v29, v0
	v_mov_b32_e32 v30, v0
	v_mov_b32_e32 v31, v0
	v_mov_b32_e32 v40, v0
	v_mov_b32_e32 v41, v0
	v_mov_b32_e32 v42, v0
	v_mov_b32_e32 v43, v0
	v_mov_b32_e32 v44, v0
	v_mov_b32_e32 v45, v0
	v_mov_b32_e32 v46, v0
	v_mov_b32_e32 v47, v0
	v_mov_b32_e32 v68, v0
	v_mov_b32_e32 v69, v0
	v_mov_b32_e32 v70, v0
	v_mov_b32_e32 v71, v0
	v_mov_b32_e32 v76, v0
	v_mov_b32_e32 v77, v0
	v_mov_b32_e32 v78, v0
	v_mov_b32_e32 v79, v0
	v_mov_b32_e32 v80, v0
	v_mov_b32_e32 v81, v0
	v_mov_b32_e32 v82, v0
	v_mov_b32_e32 v83, v0
	v_mov_b32_e32 v84, v0
	v_mov_b32_e32 v85, v0
	v_mov_b32_e32 v86, v0
	v_mov_b32_e32 v87, v0
	v_mov_b32_e32 v96, v0
	v_mov_b32_e32 v97, v0
	v_mov_b32_e32 v98, v0
	v_mov_b32_e32 v99, v0
	v_mov_b32_e32 v100, v0
	v_mov_b32_e32 v101, v0
	v_mov_b32_e32 v102, v0
	v_mov_b32_e32 v103, v0
	v_mov_b32_e32 v112, v0
	v_mov_b32_e32 v113, v0
	v_mov_b32_e32 v114, v0
	v_mov_b32_e32 v115, v0
	v_mov_b32_e32 v116, v0
	v_mov_b32_e32 v117, v0
	v_mov_b32_e32 v118, v0
	v_mov_b32_e32 v119, v0
	v_mov_b32_e32 v128, v0
	v_mov_b32_e32 v129, v0
	v_mov_b32_e32 v130, v0
	v_mov_b32_e32 v131, v0
	v_mov_b32_e32 v132, v0
	v_mov_b32_e32 v133, v0
	v_mov_b32_e32 v134, v0
	v_mov_b32_e32 v135, v0
	v_mov_b32_e32 v88, v0
	v_mov_b32_e32 v89, v0
	v_mov_b32_e32 v90, v0
	v_mov_b32_e32 v91, v0
	v_mov_b32_e32 v92, v0
	v_mov_b32_e32 v93, v0
	v_mov_b32_e32 v94, v0
	v_mov_b32_e32 v95, v0
	v_mov_b32_e32 v104, v0
	v_mov_b32_e32 v105, v0
	v_mov_b32_e32 v106, v0
	v_mov_b32_e32 v107, v0
	v_mov_b32_e32 v108, v0
	v_mov_b32_e32 v109, v0
	v_mov_b32_e32 v110, v0
	v_mov_b32_e32 v111, v0
	v_mov_b32_e32 v120, v0
	v_mov_b32_e32 v121, v0
	v_mov_b32_e32 v122, v0
	v_mov_b32_e32 v123, v0
	v_mov_b32_e32 v124, v0
	v_mov_b32_e32 v125, v0
	v_mov_b32_e32 v126, v0
	v_mov_b32_e32 v127, v0
	v_mov_b32_e32 v136, v0
	v_mov_b32_e32 v137, v0
	v_mov_b32_e32 v138, v0
	v_mov_b32_e32 v139, v0
	v_mov_b32_e32 v140, v0
	v_mov_b32_e32 v141, v0
	v_mov_b32_e32 v142, v0
	v_mov_b32_e32 v143, v0

.LBB0_205:
	s_add_i32 s5, s4, -8
	s_cmp_gt_i32 s4, 15
	s_cselect_b64 s[30:31], -1, 0
	s_lshl_b32 s19, s4, 8
	v_mov_b32_e32 v175, v145
	v_mov_b32_e32 v52, v147
	s_or_b32 s19, s19, s56
	s_cmp_gt_i32 s4, 5
	v_lshl_add_u32 v164, v52, 3, s19
	v_ashrrev_i32_e32 v165, 31, v164
	v_lshl_add_u64 v[60:61], v[164:165], 2, s[10:11]
	v_mov_b32_e32 v72, v232
	v_mov_b32_e32 v73, v233
	v_mov_b32_e32 v74, v234
	v_mov_b32_e32 v75, v235
	v_mov_b32_e32 v64, v236
	v_mov_b32_e32 v65, v237
	v_mov_b32_e32 v66, v238
	v_mov_b32_e32 v67, v239
	v_mov_b32_e32 v52, v240
	v_mov_b32_e32 v53, v241
	v_mov_b32_e32 v54, v242
	v_mov_b32_e32 v55, v243
	s_nop 0
	v_mov_b32_e32 v60, v244
	v_mov_b32_e32 v61, v245
	v_mov_b32_e32 v62, v246
	v_mov_b32_e32 v63, v247
	s_cselect_b64 s[28:29], -1, 0
	s_cmp_lt_u32 s5, 6
	s_cselect_b64 s[4:5], -1, 0
	s_or_b64 s[4:5], s[30:31], s[4:5]
	s_and_b64 s[30:31], s[28:29], s[4:5]
	v_cndmask_b32_e64 v166, 0, 1, s[30:31]
	v_cmp_ne_u32_e64 s[4:5], 1, v166
	s_andn2_b64 vcc, exec, s[30:31]
	s_waitcnt vmcnt(0)
	v_pk_add_f32 v[166:167], v[142:143], v[74:75]
	v_pk_add_f32 v[168:169], v[140:141], v[72:73]
	v_pk_add_f32 v[140:141], v[138:139], v[66:67]
	v_pk_add_f32 v[142:143], v[136:137], v[64:65]
	s_cbranch_vccnz .LBB0_207
	v_mul_f32_e32 v137, 0xbfb8aa3b, v142
	v_mul_f32_e32 v138, 0xbfb8aa3b, v169
	v_exp_f32_e32 v137, v137
	v_exp_f32_e32 v139, v138
	v_mul_f32_e32 v177, 0xbfb8aa3b, v140
	v_mul_f32_e32 v178, 0xbfb8aa3b, v167
	v_add_f32_e32 v137, 1.0, v137
	v_mul_f32_e32 v136, 0xbfb8aa3b, v168
	v_rcp_f32_e32 v138, v137
	v_add_f32_e32 v137, 1.0, v139
	v_mul_f32_e32 v139, 0xbfb8aa3b, v143
	v_mul_f32_e32 v176, 0xbfb8aa3b, v166
	v_exp_f32_e32 v177, v177
	v_exp_f32_e32 v179, v178
	v_mul_f32_e32 v178, 0xbfb8aa3b, v141
	v_exp_f32_e32 v136, v136
	v_exp_f32_e32 v139, v139
	v_exp_f32_e32 v176, v176
	v_exp_f32_e32 v180, v178
	v_add_f32_e32 v177, 1.0, v177
	v_add_f32_e32 v136, 1.0, v136
	v_add_f32_e32 v139, 1.0, v139
	v_add_f32_e32 v176, 1.0, v176
	v_rcp_f32_e32 v178, v177
	v_add_f32_e32 v177, 1.0, v179
	v_add_f32_e32 v179, 1.0, v180
	v_rcp_f32_e32 v136, v136
	v_rcp_f32_e32 v137, v137
	v_rcp_f32_e32 v176, v176
	v_rcp_f32_e32 v177, v177
	v_rcp_f32_e32 v179, v179
	v_rcp_f32_e32 v139, v139
	v_pk_mul_f32 v[168:169], v[168:169], v[136:137]
	v_pk_mul_f32 v[166:167], v[166:167], v[176:177]
	v_pk_mul_f32 v[140:141], v[140:141], v[178:179]
	v_pk_mul_f32 v[142:143], v[142:143], v[138:139]

	.amdhsa_kernel _Z6mk_fwd4Args
		.amdhsa_group_segment_fixed_size 0
		.amdhsa_private_segment_fixed_size 0
		.amdhsa_kernarg_size 456
		.amdhsa_user_sgpr_count 2
		.amdhsa_user_sgpr_dispatch_ptr 0
		.amdhsa_user_sgpr_queue_ptr 0
		.amdhsa_user_sgpr_kernarg_segment_ptr 1
		.amdhsa_user_sgpr_dispatch_id 0
		.amdhsa_user_sgpr_kernarg_preload_length 0
		.amdhsa_user_sgpr_kernarg_preload_offset 0
		.amdhsa_user_sgpr_private_segment_size 0
		.amdhsa_uses_dynamic_stack 0
		.amdhsa_enable_private_segment 0
		.amdhsa_system_sgpr_workgroup_id_x 1
		.amdhsa_system_sgpr_workgroup_id_y 0
		.amdhsa_system_sgpr_workgroup_id_z 0
		.amdhsa_system_sgpr_workgroup_info 0
		.amdhsa_system_vgpr_workitem_id 2
		.amdhsa_next_free_vgpr 256
		.amdhsa_next_free_sgpr 102
		.amdhsa_accum_offset 256
		.amdhsa_reserve_vcc 1
		.amdhsa_float_round_mode_32 0
		.amdhsa_float_round_mode_16_64 0
		.amdhsa_float_denorm_mode_32 3
		.amdhsa_float_denorm_mode_16_64 3
		.amdhsa_dx10_clamp 1
		.amdhsa_ieee_mode 1
		.amdhsa_fp16_overflow 0
		.amdhsa_tg_split 0
		.amdhsa_exception_fp_ieee_invalid_op 0
		.amdhsa_exception_fp_denorm_src 0
		.amdhsa_exception_fp_ieee_div_zero 0
		.amdhsa_exception_fp_ieee_overflow 0
		.amdhsa_exception_fp_ieee_underflow 0
		.amdhsa_exception_fp_ieee_inexact 0
		.amdhsa_exception_int_div_zero 0
	.end_amdhsa_kernel

.Lfunc_end0:
	.size	_Z6mk_fwd4Args, .Lfunc_end0-_Z6mk_fwd4Args
	.set _Z6mk_fwd4Args.num_vgpr, 256
	.set _Z6mk_fwd4Args.num_agpr, 0
	.set _Z6mk_fwd4Args.numbered_sgpr, 102
	.set _Z6mk_fwd4Args.num_named_barrier, 0
	.set _Z6mk_fwd4Args.private_seg_size, 0
	.set _Z6mk_fwd4Args.uses_vcc, 1
	.set _Z6mk_fwd4Args.uses_flat_scratch, 0
	.set _Z6mk_fwd4Args.has_dyn_sized_stack, 0
	.set _Z6mk_fwd4Args.has_recursion, 0
	.set _Z6mk_fwd4Args.has_indirect_call, 0

amdhsa.kernels:
  - .agpr_count:     0
    .args:
      - .offset:         0
        .size:           200
        .value_kind:     by_value
      - .offset:         200
        .size:           4
        .value_kind:     hidden_block_count_x
      - .offset:         204
        .size:           4
        .value_kind:     hidden_block_count_y
      - .offset:         208
        .size:           4
        .value_kind:     hidden_block_count_z
      - .offset:         212
        .size:           2
        .value_kind:     hidden_group_size_x
      - .offset:         214
        .size:           2
        .value_kind:     hidden_group_size_y
      - .offset:         216
        .size:           2
        .value_kind:     hidden_group_size_z
      - .offset:         218
        .size:           2
        .value_kind:     hidden_remainder_x
      - .offset:         220
        .size:           2
        .value_kind:     hidden_remainder_y
      - .offset:         222
        .size:           2
        .value_kind:     hidden_remainder_z
      - .offset:         240
        .size:           8
        .value_kind:     hidden_global_offset_x
      - .offset:         248
        .size:           8
        .value_kind:     hidden_global_offset_y
      - .offset:         256
        .size:           8
        .value_kind:     hidden_global_offset_z
      - .offset:         264
        .size:           2
        .value_kind:     hidden_grid_dims
      - .offset:         288
        .size:           8
        .value_kind:     hidden_multigrid_sync_arg
      - .offset:         320
        .size:           4
        .value_kind:     hidden_dynamic_lds_size
    .group_segment_fixed_size: 0
    .kernarg_segment_align: 8
    .kernarg_segment_size: 456
    .language:       OpenCL C
    .language_version:
      - 2
      - 0
    .max_flat_workgroup_size: 512
    .name:           _Z6mk_fwd4Args
    .private_segment_fixed_size: 0
    .sgpr_count:     108
    .sgpr_spill_count: 2
    .symbol:         _Z6mk_fwd4Args.kd
    .uniform_work_group_size: 1
    .uses_dynamic_stack: false
    .vgpr_count:     256
    .vgpr_spill_count: 0
    .wavefront_size: 64
